# radix select: tie shortcut (lower T when count_ge==k) and batched bitmap marking, on top of v16
# baseline (speedup 1.0000x reference)
.LBB0_503:
	v_lshl_or_b32 v21, 1, s60, v18
	s_waitcnt lgkmcnt(0)
	v_cmp_ge_u32_e64 s[12:13], v3, v21
	v_cmp_ge_u32_e64 s[14:15], v1, v21
	v_cmp_ge_u32_e64 s[16:17], v5, v21
	v_cmp_ge_u32_e64 s[18:19], v4, v21
	v_cmp_ge_u32_e64 s[20:21], v7, v21
	v_cmp_ge_u32_e64 s[22:23], v6, v21
	v_cmp_ge_u32_e64 s[24:25], v9, v21
	v_cmp_ge_u32_e64 s[26:27], v8, v21
	v_cmp_ge_u32_e64 s[28:29], v11, v21
	v_cmp_ge_u32_e64 s[30:31], v10, v21
	v_cmp_ge_u32_e64 s[34:35], v13, v21
	v_cmp_ge_u32_e64 s[36:37], v12, v21
	v_cmp_ge_u32_e64 s[38:39], v15, v21
	v_cmp_ge_u32_e64 s[40:41], v14, v21
	v_cmp_ge_u32_e64 s[66:67], v17, v21
	v_cmp_ge_u32_e32 vcc, v16, v21
	s_bcnt1_i32_b64 s12, s[12:13]
	s_bcnt1_i32_b64 s14, s[14:15]
	s_bcnt1_i32_b64 s16, s[16:17]
	s_bcnt1_i32_b64 s18, s[18:19]
	s_bcnt1_i32_b64 s20, s[20:21]
	s_bcnt1_i32_b64 s22, s[22:23]
	s_bcnt1_i32_b64 s24, s[24:25]
	s_bcnt1_i32_b64 s26, s[26:27]
	s_bcnt1_i32_b64 s28, s[28:29]
	s_bcnt1_i32_b64 s30, s[30:31]
	s_bcnt1_i32_b64 s34, s[34:35]
	s_bcnt1_i32_b64 s36, s[36:37]
	s_bcnt1_i32_b64 s38, s[38:39]
	s_bcnt1_i32_b64 s40, s[40:41]
	s_bcnt1_i32_b64 s66, s[66:67]
	s_bcnt1_i32_b64 s61, vcc
	s_add_i32 s12, s12, s14
	s_add_i32 s16, s16, s18
	s_add_i32 s20, s20, s22
	s_add_i32 s24, s24, s26
	s_add_i32 s28, s28, s30
	s_add_i32 s34, s34, s36
	s_add_i32 s38, s38, s40
	s_add_i32 s66, s66, s61
	s_add_i32 s12, s12, s16
	s_add_i32 s20, s20, s24
	s_add_i32 s28, s28, s34
	s_add_i32 s38, s38, s66
	s_add_i32 s12, s12, s20
	s_add_i32 s28, s28, s38
	s_add_i32 s12, s12, s28
	s_add_i32 s60, s60, -1
	v_cmp_gt_i32_e32 vcc, s12, v20
	s_cmp_eq_u32 s60, -1
	s_nop 0
	v_cndmask_b32_e32 v18, v18, v21, vcc
	s_cbranch_scc0 .LBB0_503
	v_cmp_ge_u32_e64 s[12:13], v3, v18
	v_cmp_ge_u32_e64 s[14:15], v1, v18
	v_cmp_ge_u32_e64 s[16:17], v5, v18
	v_cmp_ge_u32_e64 s[18:19], v4, v18
	v_cmp_ge_u32_e64 s[20:21], v7, v18
	v_cmp_ge_u32_e64 s[22:23], v6, v18
	v_cmp_ge_u32_e64 s[24:25], v9, v18
	v_cmp_ge_u32_e64 s[26:27], v8, v18
	v_cmp_ge_u32_e64 s[28:29], v11, v18
	v_cmp_ge_u32_e64 s[30:31], v10, v18
	v_cmp_ge_u32_e64 s[34:35], v13, v18
	v_cmp_ge_u32_e64 s[36:37], v12, v18
	v_cmp_ge_u32_e64 s[38:39], v15, v18
	v_cmp_ge_u32_e64 s[40:41], v14, v18
	v_cmp_ge_u32_e64 s[66:67], v17, v18
	v_cmp_ge_u32_e32 vcc, v16, v18
	s_bcnt1_i32_b64 s12, s[12:13]
	s_bcnt1_i32_b64 s14, s[14:15]
	s_bcnt1_i32_b64 s16, s[16:17]
	s_bcnt1_i32_b64 s18, s[18:19]
	s_bcnt1_i32_b64 s20, s[20:21]
	s_bcnt1_i32_b64 s22, s[22:23]
	s_bcnt1_i32_b64 s24, s[24:25]
	s_bcnt1_i32_b64 s26, s[26:27]
	s_bcnt1_i32_b64 s28, s[28:29]
	s_bcnt1_i32_b64 s30, s[30:31]
	s_bcnt1_i32_b64 s34, s[34:35]
	s_bcnt1_i32_b64 s36, s[36:37]
	s_bcnt1_i32_b64 s38, s[38:39]
	s_bcnt1_i32_b64 s40, s[40:41]
	s_bcnt1_i32_b64 s66, s[66:67]
	s_bcnt1_i32_b64 s61, vcc
	s_add_i32 s12, s12, s14
	s_add_i32 s16, s16, s18
	s_add_i32 s20, s20, s22
	s_add_i32 s24, s24, s26
	s_add_i32 s28, s28, s30
	s_add_i32 s34, s34, s36
	s_add_i32 s38, s38, s40
	s_add_i32 s66, s66, s61
	s_add_i32 s12, s12, s16
	s_add_i32 s20, s20, s24
	s_add_i32 s28, s28, s34
	s_add_i32 s38, s38, s66
	s_add_i32 s12, s12, s20
	s_add_i32 s28, s28, s38
	s_add_i32 s12, s12, s28
	s_add_i32 s12, s12, -1
	v_cmp_eq_u32_e32 vcc, s12, v20
	s_nop 1
	v_cndmask_b32_e64 v21, 0, 1, vcc
	v_sub_u32_e32 v18, v18, v21
	v_lshlrev_b32_e32 v20, 11, v19
	v_cmp_gt_u32_e32 vcc, v3, v18
	s_movk_i32 s56, 0x420
	s_xor_b64 s[62:63], s[10:11], -1
	v_sub_u32_e32 v20, v0, v20
	v_cmp_gt_u32_e64 s[12:13], v1, v18
	v_cmp_gt_u32_e64 s[14:15], v5, v18
	v_cmp_gt_u32_e64 s[16:17], v4, v18
	v_cmp_gt_u32_e64 s[18:19], v7, v18
	v_cmp_gt_u32_e64 s[20:21], v6, v18
	v_cmp_gt_u32_e64 s[22:23], v9, v18
	v_cmp_gt_u32_e64 s[24:25], v8, v18
	v_cmp_gt_u32_e64 s[26:27], v11, v18
	v_cmp_gt_u32_e64 s[28:29], v10, v18
	v_cmp_gt_u32_e64 s[30:31], v13, v18
	v_cmp_gt_u32_e64 s[34:35], v12, v18
	v_cmp_gt_u32_e64 s[36:37], v15, v18
	v_cmp_gt_u32_e64 s[38:39], v14, v18
	v_cmp_gt_u32_e64 s[40:41], v17, v18
	v_cmp_gt_u32_e64 s[66:67], v16, v18
	v_mul_lo_u32 v0, v19, s56
	s_mov_b64 s[10:11], exec
	v_lshl_add_u32 v19, v156, 1, v20
	s_and_b64 s[60:61], s[62:63], vcc
	s_and_b64 exec, s[10:11], s[60:61]
	ds_read_u16 v100, v19 offset:32768
	s_xor_b64 s[60:61], s[12:13], -1
	s_nor_b64 s[60:61], s[4:5], s[60:61]
	s_and_b64 exec, s[10:11], s[60:61]
	ds_read_u16 v101, v19 offset:32896
	s_xor_b64 s[60:61], s[14:15], -1
	s_nor_b64 s[60:61], s[74:75], s[60:61]
	s_and_b64 exec, s[10:11], s[60:61]
	ds_read_u16 v102, v19 offset:33024
	s_xor_b64 s[60:61], s[16:17], -1
	s_nor_b64 s[60:61], s[76:77], s[60:61]
	s_and_b64 exec, s[10:11], s[60:61]
	ds_read_u16 v103, v19 offset:33152
	s_xor_b64 s[60:61], s[18:19], -1
	s_nor_b64 s[60:61], s[78:79], s[60:61]
	s_and_b64 exec, s[10:11], s[60:61]
	ds_read_u16 v104, v19 offset:33280
	s_xor_b64 s[60:61], s[20:21], -1
	s_nor_b64 s[60:61], s[80:81], s[60:61]
	s_and_b64 exec, s[10:11], s[60:61]
	ds_read_u16 v105, v19 offset:33408
	s_xor_b64 s[60:61], s[22:23], -1
	s_nor_b64 s[60:61], s[82:83], s[60:61]
	s_and_b64 exec, s[10:11], s[60:61]
	ds_read_u16 v106, v19 offset:33536
	s_xor_b64 s[60:61], s[24:25], -1
	s_nor_b64 s[60:61], s[84:85], s[60:61]
	s_and_b64 exec, s[10:11], s[60:61]
	ds_read_u16 v107, v19 offset:33664
	s_xor_b64 s[60:61], s[26:27], -1
	s_nor_b64 s[60:61], s[86:87], s[60:61]
	s_and_b64 exec, s[10:11], s[60:61]
	ds_read_u16 v108, v19 offset:33792
	s_xor_b64 s[60:61], s[28:29], -1
	s_nor_b64 s[60:61], s[88:89], s[60:61]
	s_and_b64 exec, s[10:11], s[60:61]
	ds_read_u16 v109, v19 offset:33920
	s_xor_b64 s[60:61], s[30:31], -1
	s_nor_b64 s[60:61], s[90:91], s[60:61]
	s_and_b64 exec, s[10:11], s[60:61]
	ds_read_u16 v110, v19 offset:34048
	s_xor_b64 s[60:61], s[34:35], -1
	s_nor_b64 s[60:61], s[92:93], s[60:61]
	s_and_b64 exec, s[10:11], s[60:61]
	ds_read_u16 v111, v19 offset:34176
	s_xor_b64 s[60:61], s[36:37], -1
	s_nor_b64 s[60:61], s[94:95], s[60:61]
	s_and_b64 exec, s[10:11], s[60:61]
	ds_read_u16 v112, v19 offset:34304
	s_xor_b64 s[60:61], s[38:39], -1
	s_nor_b64 s[60:61], s[96:97], s[60:61]
	s_and_b64 exec, s[10:11], s[60:61]
	ds_read_u16 v113, v19 offset:34432
	s_xor_b64 s[60:61], s[40:41], -1
	s_nor_b64 s[60:61], s[6:7], s[60:61]
	s_and_b64 exec, s[10:11], s[60:61]
	ds_read_u16 v114, v19 offset:34560
	s_xor_b64 s[60:61], s[66:67], -1
	s_nor_b64 s[60:61], s[8:9], s[60:61]
	s_and_b64 exec, s[10:11], s[60:61]
	ds_read_u16 v115, v19 offset:34688
	s_mov_b64 exec, s[10:11]
	s_waitcnt lgkmcnt(0)
	s_and_b64 s[60:61], s[62:63], vcc
	s_and_b64 exec, s[10:11], s[60:61]
	v_lshrrev_b32_e32 v21, 3, v100
	v_and_b32_e32 v21, 0x1ffc, v21
	v_add_u32_e32 v21, v0, v21
	v_lshlrev_b32_e64 v100, v100, 1
	ds_or_b32 v21, v100 offset:49152
	s_xor_b64 s[60:61], s[12:13], -1
	s_nor_b64 s[60:61], s[4:5], s[60:61]
	s_and_b64 exec, s[10:11], s[60:61]
	v_lshrrev_b32_e32 v21, 3, v101
	v_and_b32_e32 v21, 0x1ffc, v21
	v_add_u32_e32 v21, v0, v21
	v_lshlrev_b32_e64 v101, v101, 1
	ds_or_b32 v21, v101 offset:49152
	s_xor_b64 s[60:61], s[14:15], -1
	s_nor_b64 s[60:61], s[74:75], s[60:61]
	s_and_b64 exec, s[10:11], s[60:61]
	v_lshrrev_b32_e32 v21, 3, v102
	v_and_b32_e32 v21, 0x1ffc, v21
	v_add_u32_e32 v21, v0, v21
	v_lshlrev_b32_e64 v102, v102, 1
	ds_or_b32 v21, v102 offset:49152
	s_xor_b64 s[60:61], s[16:17], -1
	s_nor_b64 s[60:61], s[76:77], s[60:61]
	s_and_b64 exec, s[10:11], s[60:61]
	v_lshrrev_b32_e32 v21, 3, v103
	v_and_b32_e32 v21, 0x1ffc, v21
	v_add_u32_e32 v21, v0, v21
	v_lshlrev_b32_e64 v103, v103, 1
	ds_or_b32 v21, v103 offset:49152
	s_xor_b64 s[60:61], s[18:19], -1
	s_nor_b64 s[60:61], s[78:79], s[60:61]
	s_and_b64 exec, s[10:11], s[60:61]
	v_lshrrev_b32_e32 v21, 3, v104
	v_and_b32_e32 v21, 0x1ffc, v21
	v_add_u32_e32 v21, v0, v21
	v_lshlrev_b32_e64 v104, v104, 1
	ds_or_b32 v21, v104 offset:49152
	s_xor_b64 s[60:61], s[20:21], -1
	s_nor_b64 s[60:61], s[80:81], s[60:61]
	s_and_b64 exec, s[10:11], s[60:61]
	v_lshrrev_b32_e32 v21, 3, v105
	v_and_b32_e32 v21, 0x1ffc, v21
	v_add_u32_e32 v21, v0, v21
	v_lshlrev_b32_e64 v105, v105, 1
	ds_or_b32 v21, v105 offset:49152
	s_xor_b64 s[60:61], s[22:23], -1
	s_nor_b64 s[60:61], s[82:83], s[60:61]
	s_and_b64 exec, s[10:11], s[60:61]
	v_lshrrev_b32_e32 v21, 3, v106
	v_and_b32_e32 v21, 0x1ffc, v21
	v_add_u32_e32 v21, v0, v21
	v_lshlrev_b32_e64 v106, v106, 1
	ds_or_b32 v21, v106 offset:49152
	s_xor_b64 s[60:61], s[24:25], -1
	s_nor_b64 s[60:61], s[84:85], s[60:61]
	s_and_b64 exec, s[10:11], s[60:61]
	v_lshrrev_b32_e32 v21, 3, v107
	v_and_b32_e32 v21, 0x1ffc, v21
	v_add_u32_e32 v21, v0, v21
	v_lshlrev_b32_e64 v107, v107, 1
	ds_or_b32 v21, v107 offset:49152
	s_xor_b64 s[60:61], s[26:27], -1
	s_nor_b64 s[60:61], s[86:87], s[60:61]
	s_and_b64 exec, s[10:11], s[60:61]
	v_lshrrev_b32_e32 v21, 3, v108
	v_and_b32_e32 v21, 0x1ffc, v21
	v_add_u32_e32 v21, v0, v21
	v_lshlrev_b32_e64 v108, v108, 1
	ds_or_b32 v21, v108 offset:49152
	s_xor_b64 s[60:61], s[28:29], -1
	s_nor_b64 s[60:61], s[88:89], s[60:61]
	s_and_b64 exec, s[10:11], s[60:61]
	v_lshrrev_b32_e32 v21, 3, v109
	v_and_b32_e32 v21, 0x1ffc, v21
	v_add_u32_e32 v21, v0, v21
	v_lshlrev_b32_e64 v109, v109, 1
	ds_or_b32 v21, v109 offset:49152
	s_xor_b64 s[60:61], s[30:31], -1
	s_nor_b64 s[60:61], s[90:91], s[60:61]
	s_and_b64 exec, s[10:11], s[60:61]
	v_lshrrev_b32_e32 v21, 3, v110
	v_and_b32_e32 v21, 0x1ffc, v21
	v_add_u32_e32 v21, v0, v21
	v_lshlrev_b32_e64 v110, v110, 1
	ds_or_b32 v21, v110 offset:49152
	s_xor_b64 s[60:61], s[34:35], -1
	s_nor_b64 s[60:61], s[92:93], s[60:61]
	s_and_b64 exec, s[10:11], s[60:61]
	v_lshrrev_b32_e32 v21, 3, v111
	v_and_b32_e32 v21, 0x1ffc, v21
	v_add_u32_e32 v21, v0, v21
	v_lshlrev_b32_e64 v111, v111, 1
	ds_or_b32 v21, v111 offset:49152
	s_xor_b64 s[60:61], s[36:37], -1
	s_nor_b64 s[60:61], s[94:95], s[60:61]
	s_and_b64 exec, s[10:11], s[60:61]
	v_lshrrev_b32_e32 v21, 3, v112
	v_and_b32_e32 v21, 0x1ffc, v21
	v_add_u32_e32 v21, v0, v21
	v_lshlrev_b32_e64 v112, v112, 1
	ds_or_b32 v21, v112 offset:49152
	s_xor_b64 s[60:61], s[38:39], -1
	s_nor_b64 s[60:61], s[96:97], s[60:61]
	s_and_b64 exec, s[10:11], s[60:61]
	v_lshrrev_b32_e32 v21, 3, v113
	v_and_b32_e32 v21, 0x1ffc, v21
	v_add_u32_e32 v21, v0, v21
	v_lshlrev_b32_e64 v113, v113, 1
	ds_or_b32 v21, v113 offset:49152
	s_xor_b64 s[60:61], s[40:41], -1
	s_nor_b64 s[60:61], s[6:7], s[60:61]
	s_and_b64 exec, s[10:11], s[60:61]
	v_lshrrev_b32_e32 v21, 3, v114
	v_and_b32_e32 v21, 0x1ffc, v21
	v_add_u32_e32 v21, v0, v21
	v_lshlrev_b32_e64 v114, v114, 1
	ds_or_b32 v21, v114 offset:49152
	s_xor_b64 s[60:61], s[66:67], -1
	s_nor_b64 s[60:61], s[8:9], s[60:61]
	s_and_b64 exec, s[10:11], s[60:61]
	v_lshrrev_b32_e32 v21, 3, v115
	v_and_b32_e32 v21, 0x1ffc, v21
	v_add_u32_e32 v21, v0, v21
	v_lshlrev_b32_e64 v115, v115, 1
	ds_or_b32 v21, v115 offset:49152
	s_mov_b64 exec, s[10:11]
	s_bcnt1_i32_b64 s10, vcc
	s_bcnt1_i32_b64 s11, s[12:13]
	s_bcnt1_i32_b64 s12, s[14:15]
	s_add_i32 s10, s10, s11
	s_bcnt1_i32_b64 s13, s[16:17]
	s_add_i32 s10, s10, s12
	s_bcnt1_i32_b64 s14, s[18:19]
	s_add_i32 s10, s10, s13
	s_bcnt1_i32_b64 s15, s[20:21]
	s_add_i32 s10, s10, s14
	s_bcnt1_i32_b64 s16, s[22:23]
	s_add_i32 s10, s10, s15
	s_bcnt1_i32_b64 s17, s[24:25]
	s_add_i32 s10, s10, s16
	s_bcnt1_i32_b64 s18, s[26:27]
	s_add_i32 s10, s10, s17
	s_bcnt1_i32_b64 s19, s[28:29]
	s_add_i32 s10, s10, s18
	s_bcnt1_i32_b64 s20, s[30:31]
	s_add_i32 s10, s10, s19
	s_bcnt1_i32_b64 s21, s[34:35]
	s_add_i32 s10, s10, s20
	s_bcnt1_i32_b64 s22, s[36:37]
	s_add_i32 s10, s10, s21
	s_bcnt1_i32_b64 s23, s[38:39]
	s_add_i32 s10, s10, s22
	s_bcnt1_i32_b64 s24, s[40:41]
	s_add_i32 s10, s10, s23
	s_bcnt1_i32_b64 s25, s[66:67]
	s_add_i32 s10, s10, s24
	s_add_i32 s10, s10, s25
	v_subrev_u32_e32 v2, s10, v2
	v_cmp_lt_i32_e32 vcc, 0, v2
	s_and_saveexec_b64 s[60:61], vcc
	s_cbranch_execz .LBB0_462
	v_cmp_eq_u32_e64 s[10:11], v1, v18
	s_xor_b64 s[4:5], s[4:5], -1
	v_cmp_eq_u32_e64 s[12:13], v5, v18
	s_and_b64 s[10:11], s[4:5], s[10:11]
	s_xor_b64 s[4:5], s[74:75], -1
	v_cmp_eq_u32_e64 s[14:15], v4, v18
	s_and_b64 s[12:13], s[4:5], s[12:13]
	s_xor_b64 s[4:5], s[76:77], -1
	v_cmp_eq_u32_e64 s[16:17], v7, v18
	s_and_b64 s[14:15], s[4:5], s[14:15]
	s_xor_b64 s[4:5], s[78:79], -1
	v_cmp_eq_u32_e64 s[18:19], v6, v18
	s_and_b64 s[16:17], s[4:5], s[16:17]
	s_xor_b64 s[4:5], s[80:81], -1
	v_cmp_eq_u32_e64 s[20:21], v9, v18
	s_and_b64 s[18:19], s[4:5], s[18:19]
	s_xor_b64 s[4:5], s[82:83], -1
	v_cmp_eq_u32_e64 s[22:23], v8, v18
	s_and_b64 s[20:21], s[4:5], s[20:21]
	s_xor_b64 s[4:5], s[84:85], -1
	v_cmp_eq_u32_e64 s[24:25], v11, v18
	s_and_b64 s[22:23], s[4:5], s[22:23]
	s_xor_b64 s[4:5], s[86:87], -1
	v_cmp_eq_u32_e64 s[26:27], v10, v18
	v_cmp_lt_i32_e64 s[66:67], v202, v201
	s_and_b64 s[24:25], s[4:5], s[24:25]
	s_xor_b64 s[4:5], s[88:89], -1
	v_cmp_eq_u32_e64 s[28:29], v13, v18
	v_cndmask_b32_e64 v1, v199, v202, s[66:67]
	v_cmp_lt_i32_e64 s[66:67], v203, v201
	s_and_b64 s[26:27], s[4:5], s[26:27]
	s_xor_b64 s[4:5], s[90:91], -1
	v_cmp_eq_u32_e64 s[30:31], v12, v18
	v_cndmask_b32_e64 v4, v199, v203, s[66:67]
	v_cmp_lt_i32_e64 s[66:67], v204, v201
	s_and_b64 s[28:29], s[4:5], s[28:29]
	s_xor_b64 s[4:5], s[92:93], -1
	v_cmp_eq_u32_e64 s[34:35], v15, v18
	v_cndmask_b32_e64 v5, v199, v204, s[66:67]
	v_cmp_lt_i32_e64 s[66:67], v205, v201
	s_and_b64 s[30:31], s[4:5], s[30:31]
	s_xor_b64 s[4:5], s[94:95], -1
	v_cmp_eq_u32_e64 s[36:37], v14, v18
	v_cndmask_b32_e64 v6, v199, v205, s[66:67]
	v_cmp_lt_i32_e64 s[66:67], v206, v201
	s_and_b64 s[34:35], s[4:5], s[34:35]
	s_xor_b64 s[4:5], s[96:97], -1
	v_cmp_eq_u32_e64 s[38:39], v17, v18
	v_cndmask_b32_e64 v7, v199, v206, s[66:67]
	v_cmp_lt_i32_e64 s[66:67], v207, v201
	s_and_b64 s[36:37], s[4:5], s[36:37]
	s_xor_b64 s[4:5], s[6:7], -1
	v_cmp_eq_u32_e32 vcc, v3, v18
	v_cmp_eq_u32_e64 s[40:41], v16, v18
	v_cndmask_b32_e64 v8, v199, v207, s[66:67]
	s_and_b64 s[6:7], s[4:5], s[38:39]
	s_xor_b64 s[4:5], s[8:9], -1
	v_mov_b32_e32 v19, -1
	s_mov_b32 s56, 1
	v_lshl_add_u32 v3, v156, 1, v20
	v_lshlrev_b32_e32 v1, 2, v1
	v_lshlrev_b32_e32 v4, 2, v4
	v_lshlrev_b32_e32 v5, 2, v5
	v_lshlrev_b32_e32 v6, 2, v6
	v_lshlrev_b32_e32 v7, 2, v7
	v_lshlrev_b32_e32 v8, 2, v8
	s_and_b64 s[62:63], s[62:63], vcc
	s_and_b64 s[8:9], s[4:5], s[40:41]
	s_mov_b64 s[38:39], 0
	s_branch .LBB0_539
